# v28 + LRU carry: first flag poll peeled and issued ahead of the chunk fetch, counted wait, acquire invalidate without draining the fetch
# baseline (speedup 1.0000x reference)
.LBB0_759:
	v_mov_b32_e32 v25, v204
	s_and_b64 vcc, exec, s[38:39]
	v_and_b32_e32 v24, 63, v25
	s_movk_i32 s90, 0x4000
	s_movk_i32 s91, 0x2000
	s_mov_b32 s92, 0x8000
	s_mov_b32 s93, 0xa000
	s_mov_b32 s95, 0xe000
	s_movk_i32 s50, 0x3000
	s_movk_i32 s51, 0x7000
	s_mov_b32 s56, 0x9000
	s_mov_b32 s57, 0xb000
	s_mov_b32 s58, 0xd000
	s_mov_b32 s52, 0xf000
	s_movk_i32 s53, 0x110
	s_mov_b32 s59, 0x13000
	s_mov_b32 s60, 0x19000
	s_mov_b32 s61, 0x1f000
	s_mov_b32 s63, 0x25000
	s_mov_b64 s[88:89], 0x1000
	s_mov_b32 s75, s23
	v_readlane_b32 s34, v254, 37
	v_readlane_b32 s20, v254, 32
	v_readlane_b32 s0, v255, 0
	v_readlane_b32 s2, v255, 1
	s_add_i32 s28, s0, s2
	s_ashr_i32 s29, s28, 31
	s_lshl_b64 s[28:29], s[28:29], 12
	v_readlane_b32 s2, v254, 60
	v_readlane_b32 s3, v254, 61
	s_add_u32 s22, s2, s28
	s_addc_u32 s23, s3, s29
	v_lshlrev_b32_e32 v26, 2, v24
	s_nop 1
	s_cbranch_vccnz .Lmy_lru_f
	v_readlane_b32 s2, v254, 26
	v_readlane_b32 s0, v254, 39
	s_lshl_b32 s9, s2, 8
	s_and_b32 s40, s0, -8
	s_add_i32 s28, s40, s9
	s_ashr_i32 s29, s28, 31
	s_lshl_b64 s[28:29], s[28:29], 8
	s_add_u32 s28, s36, s28
	s_addc_u32 s29, s37, s29
	v_lshlrev_b32_e32 v2, 8, v24
	v_lshl_add_u64 v[4:5], s[28:29], 0, v[2:3]
	s_mov_b64 s[28:29], 0x180000
	v_cmp_gt_u32_e64 s[38:39], s20, v24
	v_lshl_add_u64 v[4:5], v[4:5], 0, s[28:29]
	v_mov_b32_e32 v2, 0x400000
	v_readlane_b32 s3, v254, 27
	s_mov_b64 s[46:47], -1
	s_and_saveexec_b64 s[44:45], s[38:39]
	global_load_dword v6, v[4:5], off sc1
	s_or_b64 exec, exec, s[44:45]
	global_load_dword v20, v26, s[22:23] nt
	global_load_dword v21, v26, s[22:23] offset:256 nt
	global_load_dword v22, v26, s[22:23] offset:512 nt
	global_load_dword v23, v26, s[22:23] offset:768 nt
	global_load_dword v34, v26, s[22:23] offset:1024 nt
	global_load_dword v35, v26, s[22:23] offset:1280 nt
	global_load_dword v36, v26, s[22:23] offset:1536 nt
	global_load_dword v37, v26, s[22:23] offset:1792 nt
	global_load_dword v39, v26, s[22:23] offset:2048 nt
	global_load_dword v40, v26, s[22:23] offset:2304 nt
	global_load_dword v41, v26, s[22:23] offset:2560 nt
	global_load_dword v45, v26, s[22:23] offset:2816 nt
	global_load_dword v51, v26, s[22:23] offset:3072 nt
	global_load_dword v58, v26, s[22:23] offset:3328 nt
	global_load_dword v59, v26, s[22:23] offset:3584 nt
	global_load_dword v60, v26, s[22:23] offset:3840 nt
	s_waitcnt vmcnt(16)
	s_and_saveexec_b64 s[44:45], s[38:39]
	v_cmp_ne_u32_e32 vcc, 0, v6
	s_orn2_b64 s[46:47], vcc, exec
	s_or_b64 exec, exec, s[44:45]
	v_cndmask_b32_e64 v6, 0, 1, s[46:47]
	v_cmp_ne_u32_e32 vcc, 0, v6
	s_cmp_eq_u64 vcc, exec
	s_cbranch_scc1 .Lmy_lru_acq
	s_branch .LBB0_762

.Lmy_lru_acq:
	buffer_inv sc1
	s_branch .Lmy_lru_c

.Lmy_lru_c:
	s_cmp_eq_u32 s20, 0
	s_cbranch_scc1 .LBB0_769
	s_ashr_i32 s41, s40, 31
	s_lshl_b64 s[28:29], s[40:41], 9
	v_readlane_b32 s2, v255, 2
	v_readlane_b32 s3, v255, 3
	s_add_u32 s4, s2, s28
	s_addc_u32 s9, s3, s29
	v_readlane_b32 s0, v255, 6
	s_add_u32 s28, s0, s4
	v_readlane_b32 s0, v255, 4
	v_lshlrev_b32_e32 v2, 3, v24
	s_addc_u32 s29, s0, s9
	v_lshl_add_u64 v[4:5], s[28:29], 0, v[2:3]
	v_mov_b32_e32 v2, 0
	s_mov_b32 s4, s20

.LBB0_770:
	v_lshl_add_u32 v4, v24, 2, 0
	v_add_u32_e32 v4, 0x119c0, v4
	ds_write_b32 v4, v2
	s_branch .LBB0_771
.Lmy_lru_f:
	global_load_dword v20, v26, s[22:23] nt
	global_load_dword v21, v26, s[22:23] offset:256 nt
	global_load_dword v22, v26, s[22:23] offset:512 nt
	global_load_dword v23, v26, s[22:23] offset:768 nt
	global_load_dword v34, v26, s[22:23] offset:1024 nt
	global_load_dword v35, v26, s[22:23] offset:1280 nt
	global_load_dword v36, v26, s[22:23] offset:1536 nt
	global_load_dword v37, v26, s[22:23] offset:1792 nt
	global_load_dword v39, v26, s[22:23] offset:2048 nt
	global_load_dword v40, v26, s[22:23] offset:2304 nt
	global_load_dword v41, v26, s[22:23] offset:2560 nt
	global_load_dword v45, v26, s[22:23] offset:2816 nt
	global_load_dword v51, v26, s[22:23] offset:3072 nt
	global_load_dword v58, v26, s[22:23] offset:3328 nt
	global_load_dword v59, v26, s[22:23] offset:3584 nt
	global_load_dword v60, v26, s[22:23] offset:3840 nt
